# v92 + ph_gu epilogue caches the row scales rs in VGPRs across consecutive tiles of the same row block (slot loads + reductions only when pm changes)
# speedup vs baseline: 1.0011x; 1.0011x over previous
; DI int opaque_tid() { int t = threadIdx.x; asm volatile("" : "+v"(t)); return t; }
;     DI bool next(int i, Unit& u) const {
;         const long L = (long)i * G + c; if (L >= nwg) return false;
;         int wgid = (int)L; { const int q = nwg / NXCD, r = nwg % NXCD, xcd = wgid % NXCD, off = wgid / NXCD; wgid = (xcd < r ? xcd * (q + 1) : r * (q + 1) + (xcd - r) * q) + off; }
;         const int nig = WGM * nN, gid = wgid / nig, fm = gid * WGM, gsz = (nM - fm) < WGM ? (nM - fm) : WGM;
;         u.pm = fm + ((wgid % nig) % gsz); u.pn = (wgid % nig) / gsz; return true;
; template <class Epi>
; DI void gemm_phase(LAS unsigned char* lds, const Gemm g, const StaticOrder& S, const Epi& E) {
;     const int tid = opaque_tid(), wid = __builtin_amdgcn_readfirstlane(tid >> 6), lane = tid & 63, wr = wid >> 2, wc = wid & 3, fr = lane & 15, fq = lane >> 4;
;     const int K = g.K, nt = K / BK;
;     unsigned voffA[2], voffB[2];
; #pragma unroll
;     for (int i = 0; i < 2; ++i) { int R, C; stage_rc(tid * 16 + i * 8192, R, C); const int Rb = Epi::PERM ? ((R & ~31) + perm32(R & 31)) : R;
;         voffA[i] = (unsigned)(R * K + C) * 2u; voffB[i] = (unsigned)(Rb * K + C) * 2u; }
;     const size_t kstep = (size_t)(BK * 2);
;     const size_t hstep = (size_t)HALF * K * 2;
;     const size_t tstep = 2 * hstep;
;     const unsigned ldsw = (unsigned)wid * 1024u;
;     const int aoff = lds_byte(wr * 64 + fr, fq * 8), boff = lds_byte(wc * 32 + fr, fq * 8);
;     ...
;     Unit cur, nxt; int ui = 0;
;     if (!S.next(0, cur)) return;
;     f32x4 acc[2][2][4][2];
; #pragma unroll
;     for (int a = 0; a < 2; ++a)
; #pragma unroll
;         for (int b = 0; b < 2; ++b)
; #pragma unroll
;             for (int m = 0; m < 4; ++m)
; #pragma unroll
;                 for (int n = 0; n < 2; ++n) acc[a][b][m][n] = (f32x4){0.f, 0.f, 0.f, 0.f};
;     bf16x8 At[4][2], B0[2][2], B1[2][2];
;     const char* cA = (const char*)g.A + (size_t)cur.pm * tstep; const char* cB = (const char*)g.Bt + (size_t)cur.pn * tstep;
;     PG8_STAGE(PG8_SB(0, 0), cB, voffB); PG8_STAGE(PG8_SB(0, 1), cB + hstep, voffB); PG8_STAGE(PG8_SA(0, 0), cA, voffA); PG8_STAGE(PG8_SA(0, 1), cA + hstep, voffA);
;     if (wr == 1) PG8_BAR;
;     PG8_WAIT_V(2); PG8_BAR;
;     PG8_STAGE(PG8_SB(1, 0), cB + kstep, voffB); PG8_STAGE(PG8_SA(1, 0), cA + kstep, voffA); PG8_STAGE(PG8_SB(1, 1), cB + hstep + kstep, voffB);
.LBB0_692:
	s_mov_b32 s99, -1
	s_mov_b64 s[4:5], s[0:1]
	s_mov_b32 s24, s2
	v_mov_b32_e32 v11, v242
	s_cmpk_gt_i32 s24, 0x15ff
	v_readfirstlane_b32 s22, v11
	s_cbranch_scc1 .LBB0_708
	v_lshlrev_b32_e32 v1, 4, v11
	v_add_u32_e32 v2, 0x2000, v1
	v_ashrrev_i32_e32 v3, 31, v2
	v_lshrrev_b32_e32 v3, 22, v3
	s_load_dwordx2 s[4:5], s[4:5], 0xa8
	v_add_u32_e32 v3, v2, v3
	v_ashrrev_i32_e32 v10, 10, v3
	v_mul_i32_i24_e32 v3, 0x400, v10
	v_sub_u32_e32 v2, v2, v3
	v_lshrrev_b32_e32 v3, 4, v2
	s_waitcnt lgkmcnt(0)
	s_add_u32 s25, s4, 0xec00000
	v_bitop3_b32 v2, v3, v2, 32 bitop3:0x6c
	s_addc_u32 s30, s5, 0
	v_ashrrev_i32_e32 v3, 31, v2
	s_add_u32 s8, s4, s96
	v_readlane_b32 s6, v255, 7
	v_lshrrev_b32_e32 v3, 26, v3
	s_addc_u32 s9, s5, 0
	v_readlane_b32 s7, v255, 8
	v_add_u32_e32 v3, v2, v3
	s_waitcnt vmcnt(8)
	v_lshlrev_b32_e32 v4, 3, v10
	s_and_b64 s[6:7], s[6:7], exec
	v_ashrrev_i32_e32 v12, 6, v3
	v_and_b32_e32 v4, -16, v4
	s_cselect_b32 s6, 0, 0x2880000
	v_add_u32_e32 v4, v12, v4
	s_add_u32 s6, s8, s6
	v_and_b32_e32 v5, 3, v12
	v_lshrrev_b32_e32 v6, 2, v4
	v_lshlrev_b32_e32 v7, 1, v4
	v_and_b32_e32 v3, 0xc0, v3
	s_addc_u32 s7, s9, 0
	v_and_or_b32 v5, v4, s75, v5
	v_and_b32_e32 v6, 4, v6
	v_and_b32_e32 v7, 24, v7
	v_sub_u32_e32 v2, v2, v3
	s_add_u32 s31, s6, 0x800000
	v_or3_b32 v5, v5, v6, v7
	v_lshlrev_b32_e32 v6, 5, v10
	v_ashrrev_i16_sdwa v2, v247, sext(v2) dst_sel:DWORD dst_unused:UNUSED_PAD src0_sel:DWORD src1_sel:BYTE_0
	s_addc_u32 s36, s7, 0
	v_and_b32_e32 v6, 32, v6
	v_bfe_i32 v13, v2, 0, 16
	s_ashr_i32 s62, s24, 31
	v_add_lshl_u32 v2, v6, v13, 1
	s_lshr_b32 s6, s62, 29
	v_lshl_add_u32 v152, v5, 11, v2
	v_lshl_add_u32 v154, v4, 11, v2
	v_bfe_i32 v2, v11, 27, 1
	s_add_i32 s6, s24, s6
	s_ashr_i32 s17, s22, 6
	v_lshrrev_b32_e32 v2, 22, v2
	s_ashr_i32 s7, s6, 3
	s_and_b32 s6, s6, -8
	s_ashr_i32 s23, s22, 8
	s_lshl_b32 s37, s17, 10
	v_add_u32_e32 v2, v1, v2
	s_sub_i32 s6, s24, s6
	v_and_b32_e32 v2, 0xfffffc00, v2
	s_cmp_lt_i32 s6, 0
	s_movk_i32 s8, 0x2c1
	v_sub_u32_e32 v1, v1, v2
	s_cselect_b32 s8, s8, 0x2c0
	v_lshrrev_b32_e32 v2, 4, v1
	s_mul_i32 s6, s8, s6
	v_bitop3_b32 v2, v2, v1, 32 bitop3:0x6c
	v_ashrrev_i32_e32 v1, 31, v1
	s_add_i32 s6, s6, s7
	v_lshrrev_b32_e32 v1, 26, v1
	s_mul_hi_i32 s7, s6, 0x2e8ba2e9
	v_add_u32_e32 v1, v2, v1
	s_lshr_b32 s8, s7, 31
	s_ashr_i32 s7, s7, 4
	v_ashrrev_i32_e32 v14, 6, v1
	v_ashrrev_i32_e32 v1, 31, v11
	s_add_i32 s7, s7, s8
	v_lshrrev_b32_e32 v1, 26, v1
	s_lshl_b32 s8, s7, 2
	s_mulk_i32 s7, 0x58
	v_add_u32_e32 v1, v11, v1
	s_sub_i32 s6, s6, s7
	v_ashrrev_i32_e32 v15, 6, v1
	s_bfe_i32 s7, s6, 0x80000
	v_lshlrev_b32_e32 v1, 3, v15
	s_bfe_u32 s7, s7, 0x2000d
	v_and_b32_e32 v1, -16, v1
	s_add_i32 s7, s6, s7
	v_add_u32_e32 v1, v14, v1
	s_bfe_i32 s9, s7, 0x80000
	s_and_b32 s7, s7, 0xfc
	v_and_b32_e32 v3, 3, v14
	v_lshrrev_b32_e32 v4, 2, v1
	v_lshlrev_b32_e32 v5, 1, v1
	s_sub_i32 s6, s6, s7
	v_and_or_b32 v3, v1, s75, v3
	v_and_b32_e32 v4, 4, v4
	v_and_b32_e32 v5, 24, v5
	s_sext_i32_i16 s9, s9
	s_sext_i32_i8 s6, s6
	v_or3_b32 v3, v3, v4, v5
	v_mul_i32_i24_e32 v5, 64, v14
	s_lshr_b32 s12, s9, 2
	s_add_i32 s54, s8, s6
	v_sub_u32_e32 v2, v2, v5
	s_ashr_i32 s55, s54, 31
	s_bfe_i64 s[8:9], s[12:13], 0x100000
	v_lshlrev_b32_e32 v4, 5, v15
	v_ashrrev_i16_sdwa v2, v247, sext(v2) dst_sel:DWORD dst_unused:UNUSED_PAD src0_sel:DWORD src1_sel:BYTE_0
	s_lshl_b64 s[6:7], s[54:55], 19
	s_lshl_b64 s[8:9], s[8:9], 19
	v_and_b32_e32 v4, 32, v4
	v_bfe_i32 v16, v2, 0, 16
	s_add_u32 s56, s31, s8
	v_add_lshl_u32 v2, v4, v16, 1
	s_addc_u32 s57, s36, s9
	s_add_i32 s55, s37, 0
	v_lshl_add_u32 v156, v3, 11, v2
	s_add_i32 m0, s55, 0x10000
	v_lshl_add_u32 v158, v1, 11, v2
	global_load_lds_dwordx4 v156, s[56:57]
	s_add_i32 m0, s55, 0x12000
	s_add_u32 s8, s56, 0x40000
	global_load_lds_dwordx4 v152, s[56:57]
	s_addc_u32 s9, s57, 0
	s_add_i32 m0, s55, 0x14000
	v_mov_b32_e32 v157, v0
	global_load_lds_dwordx4 v156, s[8:9]
	s_add_i32 m0, s55, 0x16000
	s_add_u32 s58, s25, s6
	s_addc_u32 s59, s30, s7
	s_add_i32 s63, s55, 0x2000
	global_load_lds_dwordx4 v152, s[8:9]
	s_mov_b32 m0, s55
	s_add_u32 s6, s58, 0x40000
	global_load_lds_dwordx4 v158, s[58:59]
	s_mov_b32 m0, s63
	s_addc_u32 s7, s59, 0
	s_add_i32 s64, s55, 0x4000
	global_load_lds_dwordx4 v154, s[58:59]
	s_mov_b32 m0, s64
	s_add_i32 s65, s55, 0x6000
	global_load_lds_dwordx4 v158, s[6:7]
	s_mov_b32 m0, s65
	v_mov_b32_e32 v153, v0
	global_load_lds_dwordx4 v154, s[6:7]
	v_mov_b32_e32 v159, v0
	v_mov_b32_e32 v155, v0
	s_cmp_eq_u32 s23, 1
	v_lshl_add_u64 v[8:9], s[56:57], 0, v[156:157]
	v_lshl_add_u64 v[6:7], s[56:57], 0, v[152:153]
	v_lshl_add_u64 v[2:3], s[58:59], 0, v[158:159]
	s_cselect_b64 s[6:7], -1, 0
	s_cmp_lg_u32 s23, 1
	v_lshl_add_u64 v[4:5], s[58:59], 0, v[154:155]
	s_cbranch_scc1 .LBB0_695
	s_barrier

; DI float fsilu(float x) { return x * fsigmoid(x); }
;     DI void operator()(const f32x4 (&acc)[2][2][4][2], const Unit& u, int wr, int wc, int fr, int fq) const {
;         const int col0 = u.pn * 128 + wc * 32 + 8 * fq;
;         const int rowb = u.pm * BM + wr * 64 + fr;
;         f32x4 sl[2][4];
; #pragma unroll
;         for (int ai = 0; ai < 2; ++ai)
; #pragma unroll
;             for (int m = 0; m < 4; ++m) sl[ai][m] = *(const f32x4*)(slots + (size_t)(rowb + ai * HALF + m * 16) * 16 + 4 * fq);
;         asm volatile("" ::: "memory");
; #pragma unroll
;         for (int ai = 0; ai < 2; ++ai)
; #pragma unroll
;             for (int m = 0; m < 4; ++m) {
;                 const int row = rowb + ai * HALF + m * 16;
;                 float t = (sl[ai][m][0] + sl[ai][m][1]) + (sl[ai][m][2] + sl[ai][m][3]);
;                 t += __shfl_xor(t, 16); t += __shfl_xor(t, 32);
;                 const float rs = __builtin_amdgcn_rsqf(t * (1.0f / D) + EPS);
;                 float h[8];
; #pragma unroll
;                 for (int n = 0; n < 2; ++n)
; #pragma unroll
;                     for (int j = 0; j < 4; ++j) { const float gv = acc[ai][0][m][n][j] * rs, uv = acc[ai][1][m][n][j] * rs; h[n * 4 + j] = fsilu(gv) * uv; }
.LBB0_704:
	v_lshl_add_u32 v178, s54, 8, v1
	v_lshl_or_b32 v179, s17, 7, v185
	v_mul_lo_u32 v166, v178, s92
	v_lshlrev_b32_e32 v179, 1, v179
	s_mov_b32 s98, 0xbfb8aa3b
	s_mov_b32 s100, 1.0
	v_add_u32_e32 v166, v166, v179
	v_add_u32_e32 v167, 0x16000, v166
	v_add_u32_e32 v168, 0x2c000, v166
	v_add_u32_e32 v169, 0x42000, v166
	v_add_u32_e32 v170, 0xb0000, v166
	v_add_u32_e32 v171, 0xc6000, v166
	v_add_u32_e32 v172, 0xdc000, v166
	v_add_u32_e32 v173, 0xf2000, v166
	s_cmp_eq_u32 s99, s54
	s_cbranch_scc1 .Lgu_rs_cached
	v_lshlrev_b32_e32 v102, 6, v178
	v_mov_b32_e32 v103, 0
	v_add_u32_e32 v104, 0x2000, v102
	v_mov_b32_e32 v105, 0
	v_lshl_add_u64 v[102:103], v[160:161], 0, v[102:103]
	v_lshl_add_u64 v[104:105], v[160:161], 0, v[104:105]
	global_load_dwordx4 v[206:209], v[102:103], off
	global_load_dwordx4 v[210:213], v[102:103], off offset:1024
	global_load_dwordx4 v[214:217], v[102:103], off offset:2048
	global_load_dwordx4 v[218:221], v[102:103], off offset:3072
	global_load_dwordx4 v[222:225], v[104:105], off
	global_load_dwordx4 v[200:203], v[104:105], off offset:1024
	global_load_dwordx4 v[188:191], v[104:105], off offset:2048
	global_load_dwordx4 v[140:143], v[104:105], off offset:3072
	v_xor_b32_e32 v204, 16, v249
	v_xor_b32_e32 v205, 32, v249
	v_lshlrev_b32_e32 v204, 2, v204
	v_lshlrev_b32_e32 v205, 2, v205
	s_mov_b32 s99, s54
	s_waitcnt vmcnt(7)
	v_add_f32_e32 v206, v206, v207
	v_add_f32_e32 v208, v208, v209
	v_add_f32_e32 v206, v206, v208
	ds_bpermute_b32 v207, v204, v206
	s_waitcnt vmcnt(6)
	v_add_f32_e32 v210, v210, v211
	v_add_f32_e32 v212, v212, v213
	v_add_f32_e32 v210, v210, v212
	ds_bpermute_b32 v211, v204, v210
	s_waitcnt vmcnt(5)
	v_add_f32_e32 v214, v214, v215
	v_add_f32_e32 v216, v216, v217
	v_add_f32_e32 v214, v214, v216
	ds_bpermute_b32 v215, v204, v214
	s_waitcnt vmcnt(4)
	v_add_f32_e32 v218, v218, v219
	v_add_f32_e32 v220, v220, v221
	v_add_f32_e32 v218, v218, v220
	ds_bpermute_b32 v219, v204, v218
	s_waitcnt vmcnt(3)
	v_add_f32_e32 v222, v222, v223
	v_add_f32_e32 v224, v224, v225
	v_add_f32_e32 v222, v222, v224
	ds_bpermute_b32 v223, v204, v222
	s_waitcnt vmcnt(2)
	v_add_f32_e32 v200, v200, v201
	v_add_f32_e32 v202, v202, v203
	v_add_f32_e32 v200, v200, v202
	ds_bpermute_b32 v201, v204, v200
	s_waitcnt vmcnt(1)
	v_add_f32_e32 v188, v188, v189
	v_add_f32_e32 v190, v190, v191
	v_add_f32_e32 v188, v188, v190
	ds_bpermute_b32 v189, v204, v188
	s_waitcnt vmcnt(0)
	v_add_f32_e32 v140, v140, v141
	v_add_f32_e32 v142, v142, v143
	v_add_f32_e32 v140, v140, v142
	ds_bpermute_b32 v141, v204, v140
	s_waitcnt lgkmcnt(0)
	v_add_f32_e32 v206, v206, v207
	ds_bpermute_b32 v207, v205, v206
	v_add_f32_e32 v210, v210, v211
	ds_bpermute_b32 v211, v205, v210
	v_add_f32_e32 v214, v214, v215
	ds_bpermute_b32 v215, v205, v214
	v_add_f32_e32 v218, v218, v219
	ds_bpermute_b32 v219, v205, v218
	v_add_f32_e32 v222, v222, v223
	ds_bpermute_b32 v223, v205, v222
	v_add_f32_e32 v200, v200, v201
	ds_bpermute_b32 v201, v205, v200
	v_add_f32_e32 v188, v188, v189
	ds_bpermute_b32 v189, v205, v188
	v_add_f32_e32 v140, v140, v141
	ds_bpermute_b32 v141, v205, v140
	s_waitcnt lgkmcnt(0)
	v_add_f32_e32 v206, v206, v207
	v_add_f32_e32 v210, v210, v211
	v_add_f32_e32 v214, v214, v215
	v_add_f32_e32 v218, v218, v219
	v_add_f32_e32 v222, v222, v223
	v_add_f32_e32 v200, v200, v201
	v_add_f32_e32 v188, v188, v189
	v_add_f32_e32 v140, v140, v141
	v_fmamk_f32 v206, v206, 0x3a800000, v243
	v_fmamk_f32 v210, v210, 0x3a800000, v243
	v_fmamk_f32 v214, v214, 0x3a800000, v243
	v_fmamk_f32 v218, v218, 0x3a800000, v243
	v_fmamk_f32 v222, v222, 0x3a800000, v243
	v_fmamk_f32 v200, v200, 0x3a800000, v243
	v_fmamk_f32 v188, v188, 0x3a800000, v243
	v_fmamk_f32 v140, v140, 0x3a800000, v243
	v_rsq_f32_e32 v232, v206
	v_rsq_f32_e32 v233, v210
	v_rsq_f32_e32 v234, v214
	v_rsq_f32_e32 v235, v218
	v_rsq_f32_e32 v236, v222
	v_rsq_f32_e32 v237, v200
	v_rsq_f32_e32 v238, v188
	v_rsq_f32_e32 v239, v140
	s_nop 1
.Lgu_rs_cached:
	v_pk_mul_f32 v[136:137], v[136:137], v[232:233] op_sel_hi:[1,0]
	v_pk_mul_f32 v[138:139], v[138:139], v[232:233] op_sel_hi:[1,0]
	v_pk_mul_f32 v[128:129], v[128:129], v[232:233] op_sel_hi:[1,0]
	v_pk_mul_f32 v[130:131], v[130:131], v[232:233] op_sel_hi:[1,0]
	v_pk_mul_f32 v[206:207], v[136:137], s[98:99] op_sel_hi:[1,0]
	v_pk_mul_f32 v[208:209], v[138:139], s[98:99] op_sel_hi:[1,0]
	v_pk_mul_f32 v[210:211], v[128:129], s[98:99] op_sel_hi:[1,0]
	v_pk_mul_f32 v[212:213], v[130:131], s[98:99] op_sel_hi:[1,0]
	v_pk_mul_f32 v[82:83], v[82:83], v[232:233] op_sel_hi:[1,0]
	v_pk_mul_f32 v[84:85], v[84:85], v[232:233] op_sel_hi:[1,0]
	v_pk_mul_f32 v[124:125], v[124:125], v[232:233] op_sel_hi:[1,0]
	v_pk_mul_f32 v[126:127], v[126:127], v[232:233] op_sel_hi:[1,0]
	v_exp_f32_e32 v206, v206
	v_exp_f32_e32 v207, v207
	v_exp_f32_e32 v208, v208
	v_exp_f32_e32 v209, v209
	v_exp_f32_e32 v210, v210
	v_exp_f32_e32 v211, v211
	v_exp_f32_e32 v212, v212
	v_exp_f32_e32 v213, v213
	v_pk_add_f32 v[206:207], v[206:207], s[100:101] op_sel_hi:[1,0]
	v_pk_add_f32 v[208:209], v[208:209], s[100:101] op_sel_hi:[1,0]
	v_pk_add_f32 v[210:211], v[210:211], s[100:101] op_sel_hi:[1,0]
	v_pk_add_f32 v[212:213], v[212:213], s[100:101] op_sel_hi:[1,0]
	v_rcp_f32_e32 v206, v206
	v_rcp_f32_e32 v207, v207
	v_rcp_f32_e32 v208, v208
	v_rcp_f32_e32 v209, v209
	v_rcp_f32_e32 v210, v210
	v_rcp_f32_e32 v211, v211
	v_rcp_f32_e32 v212, v212
	v_rcp_f32_e32 v213, v213
	v_pk_mul_f32 v[206:207], v[136:137], v[206:207]
	v_pk_mul_f32 v[208:209], v[138:139], v[208:209]
	v_pk_mul_f32 v[210:211], v[128:129], v[210:211]
	v_pk_mul_f32 v[212:213], v[130:131], v[212:213]
	v_pk_mul_f32 v[206:207], v[82:83], v[206:207]
; DI unsigned pk2(float lo, float hi) { unsigned r; asm("v_cvt_pk_bf16_f32 %0, %1, %2" : "=v"(r) : "v"(lo), "v"(hi)); return r; }
; DI float fsilu(float x) { return x * fsigmoid(x); }
;     DI void operator()(const f32x4 (&acc)[2][2][4][2], const Unit& u, int wr, int wc, int fr, int fq) const {
;     ...
;         for (int ai = 0; ai < 2; ++ai)
; #pragma unroll
;             for (int m = 0; m < 4; ++m) {
;                 const int row = rowb + ai * HALF + m * 16;
;                 float t = (sl[ai][m][0] + sl[ai][m][1]) + (sl[ai][m][2] + sl[ai][m][3]);
;                 t += __shfl_xor(t, 16); t += __shfl_xor(t, 32);
;                 const float rs = __builtin_amdgcn_rsqf(t * (1.0f / D) + EPS);
;                 float h[8];
; #pragma unroll
;                 for (int n = 0; n < 2; ++n)
; #pragma unroll
;                     for (int j = 0; j < 4; ++j) { const float gv = acc[ai][0][m][n][j] * rs, uv = acc[ai][1][m][n][j] * rs; h[n * 4 + j] = fsilu(gv) * uv; }
;                 u32x4 w; w.x = pk2(h[0], h[1]); w.y = pk2(h[2], h[3]); w.z = pk2(h[4], h[5]); w.w = pk2(h[6], h[7]);
;                 *(u32x4*)(H + (size_t)row * FF + col0) = w;
	v_pk_mul_f32 v[208:209], v[84:85], v[208:209]
	v_pk_mul_f32 v[210:211], v[124:125], v[210:211]
	v_pk_mul_f32 v[212:213], v[126:127], v[212:213]
	v_cvt_pk_bf16_f32 v214, v206, v207
	v_cvt_pk_bf16_f32 v215, v208, v209
	v_cvt_pk_bf16_f32 v216, v210, v211
	v_cvt_pk_bf16_f32 v217, v212, v213
	global_store_dwordx4 v166, v[214:217], s[8:9]
	v_pk_mul_f32 v[118:119], v[118:119], v[232:233] op_sel:[0,1] op_sel_hi:[1,1]
	v_pk_mul_f32 v[120:121], v[120:121], v[232:233] op_sel:[0,1] op_sel_hi:[1,1]
	v_pk_mul_f32 v[110:111], v[110:111], v[232:233] op_sel:[0,1] op_sel_hi:[1,1]
	v_pk_mul_f32 v[112:113], v[112:113], v[232:233] op_sel:[0,1] op_sel_hi:[1,1]
	v_pk_mul_f32 v[218:219], v[118:119], s[98:99] op_sel_hi:[1,0]
	v_pk_mul_f32 v[220:221], v[120:121], s[98:99] op_sel_hi:[1,0]
	v_pk_mul_f32 v[222:223], v[110:111], s[98:99] op_sel_hi:[1,0]
	v_pk_mul_f32 v[224:225], v[112:113], s[98:99] op_sel_hi:[1,0]
	v_pk_mul_f32 v[114:115], v[114:115], v[232:233] op_sel:[0,1] op_sel_hi:[1,1]
	v_pk_mul_f32 v[116:117], v[116:117], v[232:233] op_sel:[0,1] op_sel_hi:[1,1]
	v_pk_mul_f32 v[106:107], v[106:107], v[232:233] op_sel:[0,1] op_sel_hi:[1,1]
	v_pk_mul_f32 v[108:109], v[108:109], v[232:233] op_sel:[0,1] op_sel_hi:[1,1]
	v_exp_f32_e32 v218, v218
	v_exp_f32_e32 v219, v219
	v_exp_f32_e32 v220, v220
	v_exp_f32_e32 v221, v221
	v_exp_f32_e32 v222, v222
	v_exp_f32_e32 v223, v223
	v_exp_f32_e32 v224, v224
	v_exp_f32_e32 v225, v225
	v_pk_add_f32 v[218:219], v[218:219], s[100:101] op_sel_hi:[1,0]
	v_pk_add_f32 v[220:221], v[220:221], s[100:101] op_sel_hi:[1,0]
	v_pk_add_f32 v[222:223], v[222:223], s[100:101] op_sel_hi:[1,0]
	v_pk_add_f32 v[224:225], v[224:225], s[100:101] op_sel_hi:[1,0]
	v_rcp_f32_e32 v218, v218
	v_rcp_f32_e32 v219, v219
	v_rcp_f32_e32 v220, v220
	v_rcp_f32_e32 v221, v221
	v_rcp_f32_e32 v222, v222
	v_rcp_f32_e32 v223, v223
	v_rcp_f32_e32 v224, v224
	v_rcp_f32_e32 v225, v225
	v_pk_mul_f32 v[218:219], v[118:119], v[218:219]
	v_pk_mul_f32 v[220:221], v[120:121], v[220:221]
	v_pk_mul_f32 v[222:223], v[110:111], v[222:223]
	v_pk_mul_f32 v[224:225], v[112:113], v[224:225]
	v_pk_mul_f32 v[218:219], v[114:115], v[218:219]
	v_pk_mul_f32 v[220:221], v[116:117], v[220:221]
	v_pk_mul_f32 v[222:223], v[106:107], v[222:223]
	v_pk_mul_f32 v[224:225], v[108:109], v[224:225]
	v_cvt_pk_bf16_f32 v200, v218, v219
	v_cvt_pk_bf16_f32 v201, v220, v221
	v_cvt_pk_bf16_f32 v202, v222, v223
	v_cvt_pk_bf16_f32 v203, v224, v225
	global_store_dwordx4 v167, v[200:203], s[8:9]
	v_pk_mul_f32 v[98:99], v[98:99], v[234:235] op_sel_hi:[1,0]
	v_pk_mul_f32 v[100:101], v[100:101], v[234:235] op_sel_hi:[1,0]
	v_pk_mul_f32 v[90:91], v[90:91], v[234:235] op_sel_hi:[1,0]
	v_pk_mul_f32 v[92:93], v[92:93], v[234:235] op_sel_hi:[1,0]
	v_pk_mul_f32 v[206:207], v[98:99], s[98:99] op_sel_hi:[1,0]
	v_pk_mul_f32 v[208:209], v[100:101], s[98:99] op_sel_hi:[1,0]
	v_pk_mul_f32 v[210:211], v[90:91], s[98:99] op_sel_hi:[1,0]
	v_pk_mul_f32 v[212:213], v[92:93], s[98:99] op_sel_hi:[1,0]
	v_pk_mul_f32 v[94:95], v[94:95], v[234:235] op_sel_hi:[1,0]
	v_pk_mul_f32 v[96:97], v[96:97], v[234:235] op_sel_hi:[1,0]
	v_pk_mul_f32 v[86:87], v[86:87], v[234:235] op_sel_hi:[1,0]
	v_pk_mul_f32 v[88:89], v[88:89], v[234:235] op_sel_hi:[1,0]
	v_exp_f32_e32 v206, v206
	v_exp_f32_e32 v207, v207
	v_exp_f32_e32 v208, v208
	v_exp_f32_e32 v209, v209
	v_exp_f32_e32 v210, v210
	v_exp_f32_e32 v211, v211
	v_exp_f32_e32 v212, v212
	v_exp_f32_e32 v213, v213
	v_pk_add_f32 v[206:207], v[206:207], s[100:101] op_sel_hi:[1,0]
	v_pk_add_f32 v[208:209], v[208:209], s[100:101] op_sel_hi:[1,0]
	v_pk_add_f32 v[210:211], v[210:211], s[100:101] op_sel_hi:[1,0]
	v_pk_add_f32 v[212:213], v[212:213], s[100:101] op_sel_hi:[1,0]
	v_rcp_f32_e32 v206, v206
	v_rcp_f32_e32 v207, v207
	v_rcp_f32_e32 v208, v208
	v_rcp_f32_e32 v209, v209
	v_rcp_f32_e32 v210, v210
	v_rcp_f32_e32 v211, v211
	v_rcp_f32_e32 v212, v212
	v_rcp_f32_e32 v213, v213
	v_pk_mul_f32 v[206:207], v[98:99], v[206:207]
	v_pk_mul_f32 v[208:209], v[100:101], v[208:209]
	v_pk_mul_f32 v[210:211], v[90:91], v[210:211]
	v_pk_mul_f32 v[212:213], v[92:93], v[212:213]
	v_pk_mul_f32 v[206:207], v[94:95], v[206:207]
	v_pk_mul_f32 v[208:209], v[96:97], v[208:209]
	v_pk_mul_f32 v[210:211], v[86:87], v[210:211]
	v_pk_mul_f32 v[212:213], v[88:89], v[212:213]
	v_cvt_pk_bf16_f32 v214, v206, v207
	v_cvt_pk_bf16_f32 v215, v208, v209
	v_cvt_pk_bf16_f32 v216, v210, v211
	v_cvt_pk_bf16_f32 v217, v212, v213
	global_store_dwordx4 v168, v[214:217], s[8:9]
	v_pk_mul_f32 v[78:79], v[78:79], v[234:235] op_sel:[0,1] op_sel_hi:[1,1]
	v_pk_mul_f32 v[80:81], v[80:81], v[234:235] op_sel:[0,1] op_sel_hi:[1,1]
	v_pk_mul_f32 v[70:71], v[70:71], v[234:235] op_sel:[0,1] op_sel_hi:[1,1]
	v_pk_mul_f32 v[72:73], v[72:73], v[234:235] op_sel:[0,1] op_sel_hi:[1,1]
	v_pk_mul_f32 v[218:219], v[78:79], s[98:99] op_sel_hi:[1,0]
	v_pk_mul_f32 v[220:221], v[80:81], s[98:99] op_sel_hi:[1,0]
	v_pk_mul_f32 v[222:223], v[70:71], s[98:99] op_sel_hi:[1,0]
	v_pk_mul_f32 v[224:225], v[72:73], s[98:99] op_sel_hi:[1,0]
	v_pk_mul_f32 v[74:75], v[74:75], v[234:235] op_sel:[0,1] op_sel_hi:[1,1]
	v_pk_mul_f32 v[76:77], v[76:77], v[234:235] op_sel:[0,1] op_sel_hi:[1,1]
	v_pk_mul_f32 v[66:67], v[66:67], v[234:235] op_sel:[0,1] op_sel_hi:[1,1]
	v_pk_mul_f32 v[68:69], v[68:69], v[234:235] op_sel:[0,1] op_sel_hi:[1,1]
	v_exp_f32_e32 v218, v218
	v_exp_f32_e32 v219, v219
	v_exp_f32_e32 v220, v220
	v_exp_f32_e32 v221, v221
	v_exp_f32_e32 v222, v222
	v_exp_f32_e32 v223, v223
	v_exp_f32_e32 v224, v224
	v_exp_f32_e32 v225, v225
	v_pk_add_f32 v[218:219], v[218:219], s[100:101] op_sel_hi:[1,0]
	v_pk_add_f32 v[220:221], v[220:221], s[100:101] op_sel_hi:[1,0]
; DI unsigned pk2(float lo, float hi) { unsigned r; asm("v_cvt_pk_bf16_f32 %0, %1, %2" : "=v"(r) : "v"(lo), "v"(hi)); return r; }
; DI float fsilu(float x) { return x * fsigmoid(x); }
;     DI void operator()(const f32x4 (&acc)[2][2][4][2], const Unit& u, int wr, int wc, int fr, int fq) const {
;     ...
;         for (int ai = 0; ai < 2; ++ai)
; #pragma unroll
;             for (int m = 0; m < 4; ++m) {
;                 const int row = rowb + ai * HALF + m * 16;
;                 float t = (sl[ai][m][0] + sl[ai][m][1]) + (sl[ai][m][2] + sl[ai][m][3]);
;                 t += __shfl_xor(t, 16); t += __shfl_xor(t, 32);
;                 const float rs = __builtin_amdgcn_rsqf(t * (1.0f / D) + EPS);
;                 float h[8];
; #pragma unroll
;                 for (int n = 0; n < 2; ++n)
; #pragma unroll
;                     for (int j = 0; j < 4; ++j) { const float gv = acc[ai][0][m][n][j] * rs, uv = acc[ai][1][m][n][j] * rs; h[n * 4 + j] = fsilu(gv) * uv; }
;                 u32x4 w; w.x = pk2(h[0], h[1]); w.y = pk2(h[2], h[3]); w.z = pk2(h[4], h[5]); w.w = pk2(h[6], h[7]);
;                 *(u32x4*)(H + (size_t)row * FF + col0) = w;
	v_pk_add_f32 v[222:223], v[222:223], s[100:101] op_sel_hi:[1,0]
	v_pk_add_f32 v[224:225], v[224:225], s[100:101] op_sel_hi:[1,0]
	v_rcp_f32_e32 v218, v218
	v_rcp_f32_e32 v219, v219
	v_rcp_f32_e32 v220, v220
	v_rcp_f32_e32 v221, v221
	v_rcp_f32_e32 v222, v222
	v_rcp_f32_e32 v223, v223
	v_rcp_f32_e32 v224, v224
	v_rcp_f32_e32 v225, v225
	v_pk_mul_f32 v[218:219], v[78:79], v[218:219]
	v_pk_mul_f32 v[220:221], v[80:81], v[220:221]
	v_pk_mul_f32 v[222:223], v[70:71], v[222:223]
	v_pk_mul_f32 v[224:225], v[72:73], v[224:225]
	v_pk_mul_f32 v[218:219], v[74:75], v[218:219]
	v_pk_mul_f32 v[220:221], v[76:77], v[220:221]
	v_pk_mul_f32 v[222:223], v[66:67], v[222:223]
	v_pk_mul_f32 v[224:225], v[68:69], v[224:225]
	v_cvt_pk_bf16_f32 v200, v218, v219
	v_cvt_pk_bf16_f32 v201, v220, v221
	v_cvt_pk_bf16_f32 v202, v222, v223
	v_cvt_pk_bf16_f32 v203, v224, v225
	global_store_dwordx4 v169, v[200:203], s[8:9]
	v_pk_mul_f32 v[62:63], v[62:63], v[236:237] op_sel_hi:[1,0]
	v_pk_mul_f32 v[64:65], v[64:65], v[236:237] op_sel_hi:[1,0]
	v_pk_mul_f32 v[54:55], v[54:55], v[236:237] op_sel_hi:[1,0]
	v_pk_mul_f32 v[56:57], v[56:57], v[236:237] op_sel_hi:[1,0]
	v_pk_mul_f32 v[206:207], v[62:63], s[98:99] op_sel_hi:[1,0]
	v_pk_mul_f32 v[208:209], v[64:65], s[98:99] op_sel_hi:[1,0]
	v_pk_mul_f32 v[210:211], v[54:55], s[98:99] op_sel_hi:[1,0]
	v_pk_mul_f32 v[212:213], v[56:57], s[98:99] op_sel_hi:[1,0]
	v_pk_mul_f32 v[58:59], v[58:59], v[236:237] op_sel_hi:[1,0]
	v_pk_mul_f32 v[60:61], v[60:61], v[236:237] op_sel_hi:[1,0]
	v_pk_mul_f32 v[50:51], v[50:51], v[236:237] op_sel_hi:[1,0]
	v_pk_mul_f32 v[52:53], v[52:53], v[236:237] op_sel_hi:[1,0]
	v_exp_f32_e32 v206, v206
	v_exp_f32_e32 v207, v207
	v_exp_f32_e32 v208, v208
	v_exp_f32_e32 v209, v209
	v_exp_f32_e32 v210, v210
	v_exp_f32_e32 v211, v211
	v_exp_f32_e32 v212, v212
	v_exp_f32_e32 v213, v213
	v_pk_add_f32 v[206:207], v[206:207], s[100:101] op_sel_hi:[1,0]
	v_pk_add_f32 v[208:209], v[208:209], s[100:101] op_sel_hi:[1,0]
	v_pk_add_f32 v[210:211], v[210:211], s[100:101] op_sel_hi:[1,0]
	v_pk_add_f32 v[212:213], v[212:213], s[100:101] op_sel_hi:[1,0]
	v_rcp_f32_e32 v206, v206
	v_rcp_f32_e32 v207, v207
	v_rcp_f32_e32 v208, v208
	v_rcp_f32_e32 v209, v209
	v_rcp_f32_e32 v210, v210
	v_rcp_f32_e32 v211, v211
	v_rcp_f32_e32 v212, v212
	v_rcp_f32_e32 v213, v213
	v_pk_mul_f32 v[206:207], v[62:63], v[206:207]
	v_pk_mul_f32 v[208:209], v[64:65], v[208:209]
	v_pk_mul_f32 v[210:211], v[54:55], v[210:211]
	v_pk_mul_f32 v[212:213], v[56:57], v[212:213]
	v_pk_mul_f32 v[206:207], v[58:59], v[206:207]
	v_pk_mul_f32 v[208:209], v[60:61], v[208:209]
	v_pk_mul_f32 v[210:211], v[50:51], v[210:211]
	v_pk_mul_f32 v[212:213], v[52:53], v[212:213]
	v_cvt_pk_bf16_f32 v214, v206, v207
	v_cvt_pk_bf16_f32 v215, v208, v209
	v_cvt_pk_bf16_f32 v216, v210, v211
	v_cvt_pk_bf16_f32 v217, v212, v213
	global_store_dwordx4 v170, v[214:217], s[8:9]
	v_pk_mul_f32 v[46:47], v[46:47], v[236:237] op_sel:[0,1] op_sel_hi:[1,1]
	v_pk_mul_f32 v[48:49], v[48:49], v[236:237] op_sel:[0,1] op_sel_hi:[1,1]
	v_pk_mul_f32 v[38:39], v[38:39], v[236:237] op_sel:[0,1] op_sel_hi:[1,1]
	v_pk_mul_f32 v[40:41], v[40:41], v[236:237] op_sel:[0,1] op_sel_hi:[1,1]
	v_pk_mul_f32 v[218:219], v[46:47], s[98:99] op_sel_hi:[1,0]
	v_pk_mul_f32 v[220:221], v[48:49], s[98:99] op_sel_hi:[1,0]
	v_pk_mul_f32 v[222:223], v[38:39], s[98:99] op_sel_hi:[1,0]
	v_pk_mul_f32 v[224:225], v[40:41], s[98:99] op_sel_hi:[1,0]
	v_pk_mul_f32 v[42:43], v[42:43], v[236:237] op_sel:[0,1] op_sel_hi:[1,1]
	v_pk_mul_f32 v[44:45], v[44:45], v[236:237] op_sel:[0,1] op_sel_hi:[1,1]
	v_pk_mul_f32 v[34:35], v[34:35], v[236:237] op_sel:[0,1] op_sel_hi:[1,1]
	v_pk_mul_f32 v[36:37], v[36:37], v[236:237] op_sel:[0,1] op_sel_hi:[1,1]
	v_exp_f32_e32 v218, v218
	v_exp_f32_e32 v219, v219
	v_exp_f32_e32 v220, v220
	v_exp_f32_e32 v221, v221
	v_exp_f32_e32 v222, v222
	v_exp_f32_e32 v223, v223
	v_exp_f32_e32 v224, v224
	v_exp_f32_e32 v225, v225
	v_pk_add_f32 v[218:219], v[218:219], s[100:101] op_sel_hi:[1,0]
	v_pk_add_f32 v[220:221], v[220:221], s[100:101] op_sel_hi:[1,0]
	v_pk_add_f32 v[222:223], v[222:223], s[100:101] op_sel_hi:[1,0]
	v_pk_add_f32 v[224:225], v[224:225], s[100:101] op_sel_hi:[1,0]
	v_rcp_f32_e32 v218, v218
	v_rcp_f32_e32 v219, v219
	v_rcp_f32_e32 v220, v220
	v_rcp_f32_e32 v221, v221
	v_rcp_f32_e32 v222, v222
	v_rcp_f32_e32 v223, v223
	v_rcp_f32_e32 v224, v224
	v_rcp_f32_e32 v225, v225
	v_pk_mul_f32 v[218:219], v[46:47], v[218:219]
	v_pk_mul_f32 v[220:221], v[48:49], v[220:221]
	v_pk_mul_f32 v[222:223], v[38:39], v[222:223]
	v_pk_mul_f32 v[224:225], v[40:41], v[224:225]
; DI unsigned pk2(float lo, float hi) { unsigned r; asm("v_cvt_pk_bf16_f32 %0, %1, %2" : "=v"(r) : "v"(lo), "v"(hi)); return r; }
; DI float fsilu(float x) { return x * fsigmoid(x); }
; #define PG8_BAR __builtin_amdgcn_s_barrier()
; template <class Epi>
; DI void gemm_phase(LAS unsigned char* lds, const Gemm g, const StaticOrder& S, const Epi& E) {
;     ...
;         if (!has_next) break;
; #pragma unroll
;         for (int a = 0; a < 2; ++a)
; #pragma unroll
;             for (int b = 0; b < 2; ++b)
; #pragma unroll
;                 for (int m = 0; m < 4; ++m)
; #pragma unroll
;                     for (int n = 0; n < 2; ++n) acc[a][b][m][n] = (f32x4){0.f, 0.f, 0.f, 0.f};
;         cur = nxt; cA = nA; cB = nB; ++ui;
;         if (wr == 1) PG8_BAR;
;     DI void operator()(const f32x4 (&acc)[2][2][4][2], const Unit& u, int wr, int wc, int fr, int fq) const {
;     ...
;         for (int ai = 0; ai < 2; ++ai)
; #pragma unroll
;             for (int m = 0; m < 4; ++m) {
;                 const int row = rowb + ai * HALF + m * 16;
;                 float t = (sl[ai][m][0] + sl[ai][m][1]) + (sl[ai][m][2] + sl[ai][m][3]);
;                 t += __shfl_xor(t, 16); t += __shfl_xor(t, 32);
;                 const float rs = __builtin_amdgcn_rsqf(t * (1.0f / D) + EPS);
;                 float h[8];
; #pragma unroll
;                 for (int n = 0; n < 2; ++n)
; #pragma unroll
;                     for (int j = 0; j < 4; ++j) { const float gv = acc[ai][0][m][n][j] * rs, uv = acc[ai][1][m][n][j] * rs; h[n * 4 + j] = fsilu(gv) * uv; }
;                 u32x4 w; w.x = pk2(h[0], h[1]); w.y = pk2(h[2], h[3]); w.z = pk2(h[4], h[5]); w.w = pk2(h[6], h[7]);
;                 *(u32x4*)(H + (size_t)row * FF + col0) = w;
	v_pk_mul_f32 v[218:219], v[42:43], v[218:219]
	v_pk_mul_f32 v[220:221], v[44:45], v[220:221]
	v_pk_mul_f32 v[222:223], v[34:35], v[222:223]
	v_pk_mul_f32 v[224:225], v[36:37], v[224:225]
	v_cvt_pk_bf16_f32 v200, v218, v219
	v_cvt_pk_bf16_f32 v201, v220, v221
	v_cvt_pk_bf16_f32 v202, v222, v223
	v_cvt_pk_bf16_f32 v203, v224, v225
	global_store_dwordx4 v171, v[200:203], s[8:9]
	v_pk_mul_f32 v[30:31], v[30:31], v[238:239] op_sel_hi:[1,0]
	v_pk_mul_f32 v[32:33], v[32:33], v[238:239] op_sel_hi:[1,0]
	v_pk_mul_f32 v[22:23], v[22:23], v[238:239] op_sel_hi:[1,0]
	v_pk_mul_f32 v[24:25], v[24:25], v[238:239] op_sel_hi:[1,0]
	v_pk_mul_f32 v[206:207], v[30:31], s[98:99] op_sel_hi:[1,0]
	v_pk_mul_f32 v[208:209], v[32:33], s[98:99] op_sel_hi:[1,0]
	v_pk_mul_f32 v[210:211], v[22:23], s[98:99] op_sel_hi:[1,0]
	v_pk_mul_f32 v[212:213], v[24:25], s[98:99] op_sel_hi:[1,0]
	v_pk_mul_f32 v[26:27], v[26:27], v[238:239] op_sel_hi:[1,0]
	v_pk_mul_f32 v[28:29], v[28:29], v[238:239] op_sel_hi:[1,0]
	v_pk_mul_f32 v[18:19], v[18:19], v[238:239] op_sel_hi:[1,0]
	v_pk_mul_f32 v[20:21], v[20:21], v[238:239] op_sel_hi:[1,0]
	v_exp_f32_e32 v206, v206
	v_exp_f32_e32 v207, v207
	v_exp_f32_e32 v208, v208
	v_exp_f32_e32 v209, v209
	v_exp_f32_e32 v210, v210
	v_exp_f32_e32 v211, v211
	v_exp_f32_e32 v212, v212
	v_exp_f32_e32 v213, v213
	v_pk_add_f32 v[206:207], v[206:207], s[100:101] op_sel_hi:[1,0]
	v_pk_add_f32 v[208:209], v[208:209], s[100:101] op_sel_hi:[1,0]
	v_pk_add_f32 v[210:211], v[210:211], s[100:101] op_sel_hi:[1,0]
	v_pk_add_f32 v[212:213], v[212:213], s[100:101] op_sel_hi:[1,0]
	v_rcp_f32_e32 v206, v206
	v_rcp_f32_e32 v207, v207
	v_rcp_f32_e32 v208, v208
	v_rcp_f32_e32 v209, v209
	v_rcp_f32_e32 v210, v210
	v_rcp_f32_e32 v211, v211
	v_rcp_f32_e32 v212, v212
	v_rcp_f32_e32 v213, v213
	v_pk_mul_f32 v[206:207], v[30:31], v[206:207]
	v_pk_mul_f32 v[208:209], v[32:33], v[208:209]
	v_pk_mul_f32 v[210:211], v[22:23], v[210:211]
	v_pk_mul_f32 v[212:213], v[24:25], v[212:213]
	v_pk_mul_f32 v[206:207], v[26:27], v[206:207]
	v_pk_mul_f32 v[208:209], v[28:29], v[208:209]
	v_pk_mul_f32 v[210:211], v[18:19], v[210:211]
	v_pk_mul_f32 v[212:213], v[20:21], v[212:213]
	v_cvt_pk_bf16_f32 v214, v206, v207
	v_cvt_pk_bf16_f32 v215, v208, v209
	v_cvt_pk_bf16_f32 v216, v210, v211
	v_cvt_pk_bf16_f32 v217, v212, v213
	global_store_dwordx4 v172, v[214:217], s[8:9]
	v_pk_mul_f32 v[14:15], v[14:15], v[238:239] op_sel:[0,1] op_sel_hi:[1,1]
	v_pk_mul_f32 v[16:17], v[16:17], v[238:239] op_sel:[0,1] op_sel_hi:[1,1]
	v_pk_mul_f32 v[6:7], v[6:7], v[238:239] op_sel:[0,1] op_sel_hi:[1,1]
	v_pk_mul_f32 v[8:9], v[8:9], v[238:239] op_sel:[0,1] op_sel_hi:[1,1]
	v_pk_mul_f32 v[218:219], v[14:15], s[98:99] op_sel_hi:[1,0]
	v_pk_mul_f32 v[220:221], v[16:17], s[98:99] op_sel_hi:[1,0]
	v_pk_mul_f32 v[222:223], v[6:7], s[98:99] op_sel_hi:[1,0]
	v_pk_mul_f32 v[224:225], v[8:9], s[98:99] op_sel_hi:[1,0]
	v_pk_mul_f32 v[10:11], v[10:11], v[238:239] op_sel:[0,1] op_sel_hi:[1,1]
	v_pk_mul_f32 v[12:13], v[12:13], v[238:239] op_sel:[0,1] op_sel_hi:[1,1]
	v_pk_mul_f32 v[2:3], v[2:3], v[238:239] op_sel:[0,1] op_sel_hi:[1,1]
	v_pk_mul_f32 v[4:5], v[4:5], v[238:239] op_sel:[0,1] op_sel_hi:[1,1]
	v_exp_f32_e32 v218, v218
	v_exp_f32_e32 v219, v219
	v_exp_f32_e32 v220, v220
	v_exp_f32_e32 v221, v221
	v_exp_f32_e32 v222, v222
	v_exp_f32_e32 v223, v223
	v_exp_f32_e32 v224, v224
	v_exp_f32_e32 v225, v225
	v_pk_add_f32 v[218:219], v[218:219], s[100:101] op_sel_hi:[1,0]
	v_pk_add_f32 v[220:221], v[220:221], s[100:101] op_sel_hi:[1,0]
	v_pk_add_f32 v[222:223], v[222:223], s[100:101] op_sel_hi:[1,0]
	v_pk_add_f32 v[224:225], v[224:225], s[100:101] op_sel_hi:[1,0]
	v_rcp_f32_e32 v218, v218
	v_rcp_f32_e32 v219, v219
	v_rcp_f32_e32 v220, v220
	v_rcp_f32_e32 v221, v221
	v_rcp_f32_e32 v222, v222
	v_rcp_f32_e32 v223, v223
	v_rcp_f32_e32 v224, v224
	v_rcp_f32_e32 v225, v225
	v_pk_mul_f32 v[218:219], v[14:15], v[218:219]
	v_pk_mul_f32 v[220:221], v[16:17], v[220:221]
	v_pk_mul_f32 v[222:223], v[6:7], v[222:223]
	v_pk_mul_f32 v[224:225], v[8:9], v[224:225]
	v_pk_mul_f32 v[218:219], v[10:11], v[218:219]
	v_pk_mul_f32 v[220:221], v[12:13], v[220:221]
	v_pk_mul_f32 v[222:223], v[2:3], v[222:223]
	v_pk_mul_f32 v[224:225], v[4:5], v[224:225]
	v_cvt_pk_bf16_f32 v200, v218, v219
	v_cvt_pk_bf16_f32 v201, v220, v221
	v_cvt_pk_bf16_f32 v202, v222, v223
	v_cvt_pk_bf16_f32 v203, v224, v225
	global_store_dwordx4 v173, v[200:203], s[8:9]
	s_andn2_b64 vcc, exec, s[4:5]
	s_mov_b64 s[4:5], -1
	s_cbranch_vccnz .LBB0_697
	s_andn2_b64 vcc, exec, s[6:7]
	s_cbranch_vccnz .LBB0_696
	s_barrier
	s_branch .LBB0_696
